# v084: v081 + nt (streaming) hint on the read-once f32 weight loads of the prologue transpose-convert
# speedup vs baseline: 1.0144x; 1.0144x over previous
.LBB0_200:
	s_cmp_lt_i32 s11, s53
	v_ashrrev_i32_e32 v136, 4, v133
	v_cmp_lt_i32_e32 vcc, -1, v130
	s_cselect_b64 s[6:7], -1, 0
	s_cmp_ge_i32 s11, s53
	v_lshl_add_u64 v[134:135], v[130:131], 2, s[70:71]
	s_cbranch_scc1 .LBB0_210
	v_add_u32_e32 v82, s86, v136
	v_mov_b32_e32 v70, 0
	v_mov_b32_e32 v66, 0
	v_mov_b32_e32 v67, 0
	v_mov_b32_e32 v68, 0
	v_mov_b32_e32 v69, 0
	s_and_saveexec_b64 s[8:9], vcc
	s_cbranch_execz .LBB0_203
	v_ashrrev_i32_e32 v66, 31, v82
	v_mul_lo_u32 v68, s75, v82
	v_mul_lo_u32 v69, s74, v66
	v_mad_u64_u32 v[66:67], s[88:89], s74, v82, 0
	v_add3_u32 v67, v67, v69, v68
	v_lshl_add_u64 v[66:67], v[66:67], 2, v[134:135]
	global_load_dwordx4 v[66:69], v[66:67], off nt
.LBB0_203:
	s_or_b64 exec, exec, s[8:9]
	v_mov_b32_e32 v71, 0
	v_mov_b32_e32 v72, 0
	v_mov_b32_e32 v73, 0
	s_and_saveexec_b64 s[8:9], vcc
	s_cbranch_execz .LBB0_205
	v_add_u32_e32 v70, 32, v82
	v_ashrrev_i32_e32 v71, 31, v70
	v_mul_lo_u32 v72, s74, v71
	v_mul_lo_u32 v73, s75, v70
	v_mad_u64_u32 v[70:71], s[88:89], s74, v70, 0
	v_add3_u32 v71, v71, v72, v73
	v_lshl_add_u64 v[70:71], v[70:71], 2, v[134:135]
	global_load_dwordx4 v[70:73], v[70:71], off nt
.LBB0_205:
	s_or_b64 exec, exec, s[8:9]
	v_mov_b32_e32 v77, 0
	v_mov_b32_e32 v78, 0
	v_mov_b32_e32 v79, 0
	v_mov_b32_e32 v80, 0
	v_mov_b32_e32 v81, 0
	s_and_saveexec_b64 s[8:9], vcc
	s_cbranch_execz .LBB0_207
	v_add_u32_e32 v74, 64, v82
	v_ashrrev_i32_e32 v75, 31, v74
	v_mul_lo_u32 v76, s74, v75
	v_mul_lo_u32 v78, s75, v74
	v_mad_u64_u32 v[74:75], s[88:89], s74, v74, 0
	v_add3_u32 v75, v75, v76, v78
	v_lshl_add_u64 v[74:75], v[74:75], 2, v[134:135]
	global_load_dwordx4 v[78:81], v[74:75], off nt
.LBB0_207:
	s_or_b64 exec, exec, s[8:9]
	v_mov_b32_e32 v76, 0
	v_mov_b32_e32 v75, 0
	v_mov_b32_e32 v74, 0
	s_and_saveexec_b64 s[8:9], vcc
	s_cbranch_execz .LBB0_209
	v_add_u32_e32 v74, 0x60, v82
	v_ashrrev_i32_e32 v75, 31, v74
	v_mul_lo_u32 v76, s74, v75
	v_mul_lo_u32 v77, s75, v74
	v_mad_u64_u32 v[74:75], s[88:89], s74, v74, 0
	v_add3_u32 v75, v75, v76, v77
	v_lshl_add_u64 v[74:75], v[74:75], 2, v[134:135]
	global_load_dwordx4 v[74:77], v[74:75], off nt

.LBB0_210:
	s_cmp_lt_i32 s10, s53
	s_cselect_b64 s[8:9], -1, 0
	s_cmp_ge_i32 s10, s53
	s_cbranch_scc1 .LBB0_220
	v_add_u32_e32 v98, s0, v136
	v_mov_b32_e32 v86, 0
	v_mov_b32_e32 v82, 0
	v_mov_b32_e32 v83, 0
	v_mov_b32_e32 v84, 0
	v_mov_b32_e32 v85, 0
	s_and_saveexec_b64 s[10:11], vcc
	s_cbranch_execz .LBB0_213
	v_ashrrev_i32_e32 v82, 31, v98
	v_mul_lo_u32 v84, s75, v98
	v_mul_lo_u32 v85, s74, v82
	v_mad_u64_u32 v[82:83], s[88:89], s74, v98, 0
	v_add3_u32 v83, v83, v85, v84
	v_lshl_add_u64 v[82:83], v[82:83], 2, v[134:135]
	global_load_dwordx4 v[82:85], v[82:83], off nt
.LBB0_213:
	s_or_b64 exec, exec, s[10:11]
	v_mov_b32_e32 v87, 0
	v_mov_b32_e32 v88, 0
	v_mov_b32_e32 v89, 0
	s_and_saveexec_b64 s[10:11], vcc
	s_cbranch_execz .LBB0_215
	v_add_u32_e32 v86, 32, v98
	v_ashrrev_i32_e32 v87, 31, v86
	v_mul_lo_u32 v88, s74, v87
	v_mul_lo_u32 v89, s75, v86
	v_mad_u64_u32 v[86:87], s[88:89], s74, v86, 0
	v_add3_u32 v87, v87, v88, v89
	v_lshl_add_u64 v[86:87], v[86:87], 2, v[134:135]
	global_load_dwordx4 v[86:89], v[86:87], off nt
.LBB0_215:
	s_or_b64 exec, exec, s[10:11]
	v_mov_b32_e32 v93, 0
	v_mov_b32_e32 v94, 0
	v_mov_b32_e32 v95, 0
	v_mov_b32_e32 v96, 0
	v_mov_b32_e32 v97, 0
	s_and_saveexec_b64 s[10:11], vcc
	s_cbranch_execz .LBB0_217
	v_add_u32_e32 v90, 64, v98
	v_ashrrev_i32_e32 v91, 31, v90
	v_mul_lo_u32 v92, s74, v91
	v_mul_lo_u32 v94, s75, v90
	v_mad_u64_u32 v[90:91], s[88:89], s74, v90, 0
	v_add3_u32 v91, v91, v92, v94
	v_lshl_add_u64 v[90:91], v[90:91], 2, v[134:135]
	global_load_dwordx4 v[94:97], v[90:91], off nt
.LBB0_217:
	s_or_b64 exec, exec, s[10:11]
	v_mov_b32_e32 v92, 0
	v_mov_b32_e32 v91, 0
	v_mov_b32_e32 v90, 0
	s_and_saveexec_b64 s[10:11], vcc
	s_cbranch_execz .LBB0_219
	v_add_u32_e32 v90, 0x60, v98
	v_ashrrev_i32_e32 v91, 31, v90
	v_mul_lo_u32 v92, s74, v91
	v_mul_lo_u32 v93, s75, v90
	v_mad_u64_u32 v[90:91], s[88:89], s74, v90, 0
	v_add3_u32 v91, v91, v92, v93
	v_lshl_add_u64 v[90:91], v[90:91], 2, v[134:135]
	global_load_dwordx4 v[90:93], v[90:91], off nt

.LBB0_220:
	s_cmp_lt_i32 s13, s53
	s_cselect_b64 s[88:89], -1, 0
	s_cmp_ge_i32 s13, s53
	s_cbranch_scc1 .LBB0_230
	v_add_u32_e32 v114, s84, v136
	v_mov_b32_e32 v102, 0
	v_mov_b32_e32 v98, 0
	v_mov_b32_e32 v99, 0
	v_mov_b32_e32 v100, 0
	v_mov_b32_e32 v101, 0
	s_and_saveexec_b64 s[10:11], vcc
	s_cbranch_execz .LBB0_223
	v_ashrrev_i32_e32 v98, 31, v114
	v_mul_lo_u32 v100, s75, v114
	v_mul_lo_u32 v101, s74, v98
	v_mad_u64_u32 v[98:99], s[90:91], s74, v114, 0
	v_add3_u32 v99, v99, v101, v100
	v_lshl_add_u64 v[98:99], v[98:99], 2, v[134:135]
	global_load_dwordx4 v[98:101], v[98:99], off nt
.LBB0_223:
	s_or_b64 exec, exec, s[10:11]
	v_mov_b32_e32 v103, 0
	v_mov_b32_e32 v104, 0
	v_mov_b32_e32 v105, 0
	s_and_saveexec_b64 s[10:11], vcc
	s_cbranch_execz .LBB0_225
	v_add_u32_e32 v102, 32, v114
	v_ashrrev_i32_e32 v103, 31, v102
	v_mul_lo_u32 v104, s74, v103
	v_mul_lo_u32 v105, s75, v102
	v_mad_u64_u32 v[102:103], s[90:91], s74, v102, 0
	v_add3_u32 v103, v103, v104, v105
	v_lshl_add_u64 v[102:103], v[102:103], 2, v[134:135]
	global_load_dwordx4 v[102:105], v[102:103], off nt
.LBB0_225:
	s_or_b64 exec, exec, s[10:11]
	v_mov_b32_e32 v109, 0
	v_mov_b32_e32 v110, 0
	v_mov_b32_e32 v111, 0
	v_mov_b32_e32 v112, 0
	v_mov_b32_e32 v113, 0
	s_and_saveexec_b64 s[10:11], vcc
	s_cbranch_execz .LBB0_227
	v_add_u32_e32 v106, 64, v114
	v_ashrrev_i32_e32 v107, 31, v106
	v_mul_lo_u32 v108, s74, v107
	v_mul_lo_u32 v110, s75, v106
	v_mad_u64_u32 v[106:107], s[90:91], s74, v106, 0
	v_add3_u32 v107, v107, v108, v110
	v_lshl_add_u64 v[106:107], v[106:107], 2, v[134:135]
	global_load_dwordx4 v[110:113], v[106:107], off nt
.LBB0_227:
	s_or_b64 exec, exec, s[10:11]
	v_mov_b32_e32 v108, 0
	v_mov_b32_e32 v107, 0
	v_mov_b32_e32 v106, 0
	s_and_saveexec_b64 s[10:11], vcc
	s_cbranch_execz .LBB0_229
	v_add_u32_e32 v106, 0x60, v114
	v_ashrrev_i32_e32 v107, 31, v106
	v_mul_lo_u32 v108, s74, v107
	v_mul_lo_u32 v109, s75, v106
	v_mad_u64_u32 v[106:107], s[90:91], s74, v106, 0
	v_add3_u32 v107, v107, v108, v109
	v_lshl_add_u64 v[106:107], v[106:107], 2, v[134:135]
	global_load_dwordx4 v[106:109], v[106:107], off nt

.LBB0_230:
	s_cmp_lt_i32 s12, s53
	s_cselect_b64 s[90:91], -1, 0
	s_cmp_ge_i32 s12, s53
	s_cbranch_scc1 .LBB0_240
	v_add_u32_e32 v130, s82, v136
	v_mov_b32_e32 v118, 0
	v_mov_b32_e32 v114, 0
	v_mov_b32_e32 v115, 0
	v_mov_b32_e32 v116, 0
	v_mov_b32_e32 v117, 0
	s_and_saveexec_b64 s[10:11], vcc
	s_cbranch_execz .LBB0_233
	v_ashrrev_i32_e32 v114, 31, v130
	v_mul_lo_u32 v116, s75, v130
	v_mul_lo_u32 v117, s74, v114
	v_mad_u64_u32 v[114:115], s[12:13], s74, v130, 0
	v_add3_u32 v115, v115, v117, v116
	v_lshl_add_u64 v[114:115], v[114:115], 2, v[134:135]
	global_load_dwordx4 v[114:117], v[114:115], off nt
.LBB0_233:
	s_or_b64 exec, exec, s[10:11]
	v_mov_b32_e32 v119, 0
	v_mov_b32_e32 v120, 0
	v_mov_b32_e32 v121, 0
	s_and_saveexec_b64 s[10:11], vcc
	s_cbranch_execz .LBB0_235
	v_add_u32_e32 v118, 32, v130
	v_ashrrev_i32_e32 v119, 31, v118
	v_mul_lo_u32 v120, s74, v119
	v_mul_lo_u32 v121, s75, v118
	v_mad_u64_u32 v[118:119], s[12:13], s74, v118, 0
	v_add3_u32 v119, v119, v120, v121
	v_lshl_add_u64 v[118:119], v[118:119], 2, v[134:135]
	global_load_dwordx4 v[118:121], v[118:119], off nt
.LBB0_235:
	s_or_b64 exec, exec, s[10:11]
	v_mov_b32_e32 v125, 0
	v_mov_b32_e32 v126, 0
	v_mov_b32_e32 v127, 0
	v_mov_b32_e32 v128, 0
	v_mov_b32_e32 v129, 0
	s_and_saveexec_b64 s[10:11], vcc
	s_cbranch_execz .LBB0_237
	v_add_u32_e32 v122, 64, v130
	v_ashrrev_i32_e32 v123, 31, v122
	v_mul_lo_u32 v124, s74, v123
	v_mul_lo_u32 v126, s75, v122
	v_mad_u64_u32 v[122:123], s[12:13], s74, v122, 0
	v_add3_u32 v123, v123, v124, v126
	v_lshl_add_u64 v[122:123], v[122:123], 2, v[134:135]
	global_load_dwordx4 v[126:129], v[122:123], off nt
.LBB0_237:
	s_or_b64 exec, exec, s[10:11]
	v_mov_b32_e32 v124, 0
	v_mov_b32_e32 v123, 0
	v_mov_b32_e32 v122, 0
	s_and_saveexec_b64 s[10:11], vcc
	s_cbranch_execz .LBB0_239
	v_add_u32_e32 v122, 0x60, v130
	v_ashrrev_i32_e32 v123, 31, v122
	v_mul_lo_u32 v124, s74, v123
	v_mul_lo_u32 v125, s75, v122
	v_mad_u64_u32 v[122:123], s[12:13], s74, v122, 0
	v_add3_u32 v123, v123, v124, v125
	v_lshl_add_u64 v[122:123], v[122:123], 2, v[134:135]
	global_load_dwordx4 v[122:125], v[122:123], off nt
